# code placement: attention tile MFMAs on 8-byte boundaries via _e64 encodings of one VALU per odd gap (44 of 48 aligned)
# baseline (speedup 1.0000x reference)
.LBB0_40:
	s_add_i32 s60, s59, 0
	v_add_u32_e32 v144, s60, v196
	ds_read_b128 v[188:191], v144
	ds_read_b128 v[200:203], v197
	v_xad_u32 v144, v196, 32, s60
	ds_read_b128 v[204:207], v144
	v_xor_b32_e32 v199, 32, v197
	ds_read_b128 v[216:219], v199
	v_xad_u32 v144, v196, 64, s60
	ds_read_b128 v[220:223], v144
	v_xor_b32_e32 v199, 64, v197
	ds_read_b128 v[224:227], v199
	s_waitcnt lgkmcnt(4)
	v_mfma_f32_32x32x16_bf16 v[128:143], v[188:191], v[200:203], 0
	v_xor_b32_e32 v144, 0x60, v196
	v_add_u32_e32 v144, s60, v144
	ds_read_b128 v[188:191], v144
	v_xor_b32_e32 v199, 0x60, v197
	ds_read_b128 v[200:203], v199
	s_waitcnt lgkmcnt(4)
	v_mfma_f32_32x32x16_bf16 v[128:143], v[204:207], v[216:219], v[128:143]
	v_xor_b32_e32 v144, 0x80, v196
	v_add_u32_e32 v144, s60, v144
	ds_read_b128 v[204:207], v144
	v_xor_b32_e32 v199, 0x80, v197
	ds_read_b128 v[216:219], v199
	s_waitcnt lgkmcnt(4)
	v_mfma_f32_32x32x16_bf16 v[128:143], v[220:223], v[224:227], v[128:143]
	v_xor_b32_e32 v144, 0xa0, v196
	v_add_u32_e32 v144, s60, v144
	ds_read_b128 v[220:223], v144
	v_xor_b32_e32 v199, 0xa0, v197
	ds_read_b128 v[224:227], v199
	s_waitcnt lgkmcnt(4)
	v_mfma_f32_32x32x16_bf16 v[128:143], v[188:191], v[200:203], v[128:143]
	v_xor_b32_e32 v144, 0xc0, v196
	v_add_u32_e32 v144, s60, v144
	ds_read_b128 v[188:191], v144
	v_xor_b32_e32 v199, 0xc0, v197
	ds_read_b128 v[200:203], v199
	s_waitcnt lgkmcnt(4)
	v_mfma_f32_32x32x16_bf16 v[156:171], v[204:207], v[216:219], 0
	v_xor_b32_e32 v144, 0xe0, v196
	v_add_u32_e32 v144, s60, v144
	ds_read_b128 v[204:207], v144
	v_xor_b32_e32 v199, 0xe0, v197
	ds_read_b128 v[216:219], v199
	s_waitcnt lgkmcnt(4)
	v_mfma_f32_32x32x16_bf16 v[156:171], v[220:223], v[224:227], v[156:171]
	v_add_u32_e32 v144, s60, v196
	ds_read_b128 v[220:223], v144 offset:8192
	ds_read_b128 v[224:227], v197
	v_exp_f32_e32 v128, v128
	v_exp_f32_e32 v129, v129
	v_exp_f32_e64 v130, v130
	s_waitcnt lgkmcnt(4)
	v_mfma_f32_32x32x16_bf16 v[156:171], v[188:191], v[200:203], v[156:171]
	v_xad_u32 v144, v196, 32, s60
	ds_read_b128 v[188:191], v144 offset:8192
	v_xor_b32_e32 v199, 32, v197
	ds_read_b128 v[200:203], v199
	v_exp_f32_e32 v131, v131
	v_exp_f32_e32 v132, v132
	v_exp_f32_e64 v133, v133
	s_waitcnt lgkmcnt(4)
	v_mfma_f32_32x32x16_bf16 v[156:171], v[204:207], v[216:219], v[156:171]
	v_xad_u32 v144, v196, 64, s60
	ds_read_b128 v[204:207], v144 offset:8192
	v_xor_b32_e32 v199, 64, v197
	ds_read_b128 v[216:219], v199
	v_exp_f32_e32 v134, v134
	v_exp_f32_e32 v135, v135
	v_exp_f32_e64 v136, v136
	s_waitcnt lgkmcnt(4)
	v_mfma_f32_32x32x16_bf16 v[172:187], v[220:223], v[224:227], 0
	v_xor_b32_e32 v144, 0x60, v196
	v_add_u32_e32 v144, s60, v144
	ds_read_b128 v[220:223], v144 offset:8192
	v_xor_b32_e32 v199, 0x60, v197
	ds_read_b128 v[224:227], v199
	v_exp_f32_e32 v137, v137
	v_exp_f32_e32 v138, v138
	v_exp_f32_e64 v139, v139
	s_waitcnt lgkmcnt(4)
	v_mfma_f32_32x32x16_bf16 v[172:187], v[188:191], v[200:203], v[172:187]
	v_xor_b32_e32 v144, 0x80, v196
	v_add_u32_e32 v144, s60, v144
	ds_read_b128 v[188:191], v144 offset:8192
	v_xor_b32_e32 v199, 0x80, v197
	ds_read_b128 v[200:203], v199
	v_exp_f32_e32 v140, v140
	v_exp_f32_e32 v141, v141
	v_exp_f32_e64 v142, v142
	s_waitcnt lgkmcnt(4)
	v_mfma_f32_32x32x16_bf16 v[172:187], v[204:207], v[216:219], v[172:187]
	v_xor_b32_e32 v144, 0xa0, v196
	v_add_u32_e32 v144, s60, v144
	ds_read_b128 v[204:207], v144 offset:8192
	v_xor_b32_e32 v199, 0xa0, v197
	ds_read_b128 v[216:219], v199
	v_exp_f32_e32 v143, v143
	v_add_f32_e32 v192, v128, v129
	v_add_f32_e32 v193, v130, v131
	v_add_f32_e32 v192, v192, v132
	v_add_f32_e32 v193, v193, v133
	v_add_f32_e32 v192, v192, v134
	s_waitcnt lgkmcnt(4)
	v_mfma_f32_32x32x16_bf16 v[172:187], v[220:223], v[224:227], v[172:187]
	v_xor_b32_e32 v144, 0xc0, v196
	v_add_u32_e32 v144, s60, v144
	ds_read_b128 v[220:223], v144 offset:8192
	v_xor_b32_e32 v199, 0xc0, v197
	ds_read_b128 v[224:227], v199
	v_add_f32_e32 v193, v193, v135
	v_add_f32_e32 v192, v192, v136
	v_add_f32_e32 v193, v193, v137
	v_add_f32_e32 v192, v192, v138
	v_add_f32_e32 v193, v193, v139
	v_add_f32_e32 v192, v192, v140
	v_add_f32_e64 v193, v193, v141
	s_waitcnt lgkmcnt(4)
	v_mfma_f32_32x32x16_bf16 v[228:243], v[188:191], v[200:203], 0
	v_xor_b32_e32 v144, 0xe0, v196
	v_add_u32_e32 v144, s60, v144
	ds_read_b128 v[188:191], v144 offset:8192
	v_xor_b32_e32 v199, 0xe0, v197
	ds_read_b128 v[200:203], v199
	v_add_f32_e32 v192, v192, v142
	v_add_f32_e32 v193, v193, v143
	v_add_f32_e32 v192, v192, v193
	v_add_f32_e32 v150, v150, v192
	v_cvt_pk_bf16_f32 v128, v128, v129
	v_cvt_pk_bf16_f32 v129, v130, v131
	v_cvt_pk_bf16_f32 v130, v132, v133
	s_waitcnt lgkmcnt(4)
	v_mfma_f32_32x32x16_bf16 v[228:243], v[204:207], v[216:219], v[228:243]
	v_add_u32_e32 v248, s60, v198
	v_xad_u32 v249, v198, 32, s60
	ds_read_b128 v[204:207], v248
	ds_read_b128 v[216:219], v249
	v_cvt_pk_bf16_f32 v131, v134, v135
	v_cvt_pk_bf16_f32 v132, v136, v137
	v_cvt_pk_bf16_f32 v133, v138, v139
	v_cvt_pk_bf16_f32 v134, v140, v141
	v_cvt_pk_bf16_f32 v135, v142, v143
	v_exp_f32_e64 v156, v156
	s_waitcnt lgkmcnt(4)
	v_mfma_f32_32x32x16_bf16 v[228:243], v[220:223], v[224:227], v[228:243]
	ds_read_b128 v[220:223], v248 offset:4096
	ds_read_b128 v[224:227], v249 offset:4096
	v_exp_f32_e32 v157, v157
	v_exp_f32_e32 v158, v158
	v_exp_f32_e32 v159, v159
	s_waitcnt lgkmcnt(4)
	v_mfma_f32_32x32x16_bf16 v[228:243], v[188:191], v[200:203], v[228:243]
	ds_read_b128 v[188:191], v248 offset:8192
	ds_read_b128 v[200:203], v249 offset:8192
	v_exp_f32_e32 v160, v160
	v_exp_f32_e32 v161, v161
	v_exp_f32_e32 v162, v162
	s_waitcnt lgkmcnt(4)
	v_mfma_f32_32x32x16_bf16 v[112:127], v[204:207], v[128:131], v[112:127]
	v_exp_f32_e32 v163, v163
	v_exp_f32_e32 v164, v164
	v_exp_f32_e64 v165, v165
	v_mfma_f32_32x32x16_bf16 v[112:127], v[216:219], v[132:135], v[112:127]
	ds_read_b128 v[204:207], v248 offset:12288
	ds_read_b128 v[216:219], v249 offset:12288
	v_exp_f32_e32 v166, v166
	v_exp_f32_e32 v167, v167
	v_exp_f32_e32 v168, v168
	s_waitcnt lgkmcnt(4)
	v_mfma_f32_32x32x16_bf16 v[80:95], v[220:223], v[128:131], v[80:95]
	v_exp_f32_e32 v169, v169
	v_exp_f32_e32 v170, v170
	v_exp_f32_e32 v171, v171
	v_add_f32_e32 v192, v156, v157
	v_mfma_f32_32x32x16_bf16 v[80:95], v[224:227], v[132:135], v[80:95]
	ds_read_b128 v[220:223], v248
	ds_read_b128 v[224:227], v249
	v_add_f32_e32 v193, v158, v159
	v_add_f32_e32 v192, v192, v160
	v_add_f32_e32 v193, v193, v161
	v_add_f32_e32 v192, v192, v162
	v_add_f32_e32 v193, v193, v163
	v_add_f32_e32 v192, v192, v164
	v_add_f32_e32 v193, v193, v165
	s_waitcnt lgkmcnt(4)
	v_mfma_f32_32x32x16_bf16 v[48:63], v[188:191], v[128:131], v[48:63]
	v_add_f32_e32 v192, v192, v166
	v_add_f32_e32 v193, v193, v167
	v_add_f32_e32 v192, v192, v168
	v_add_f32_e32 v193, v193, v169
	v_add_f32_e32 v192, v192, v170
	v_add_f32_e32 v193, v193, v171
	v_add_f32_e64 v192, v192, v193
	v_mfma_f32_32x32x16_bf16 v[48:63], v[200:203], v[132:135], v[48:63]
	ds_read_b128 v[188:191], v248 offset:4096
	ds_read_b128 v[200:203], v249 offset:4096
	v_add_f32_e32 v151, v151, v192
	v_cvt_pk_bf16_f32 v156, v156, v157
	v_cvt_pk_bf16_f32 v157, v158, v159
	v_cvt_pk_bf16_f32 v158, v160, v161
	v_cvt_pk_bf16_f32 v159, v162, v163
	v_cvt_pk_bf16_f32 v160, v164, v165
	v_cvt_pk_bf16_f32 v161, v166, v167
	s_waitcnt lgkmcnt(4)
	v_mfma_f32_32x32x16_bf16 v[16:31], v[204:207], v[128:131], v[16:31]
	v_cvt_pk_bf16_f32 v162, v168, v169
	v_cvt_pk_bf16_f32 v163, v170, v171
	v_exp_f32_e32 v172, v172
	v_exp_f32_e32 v173, v173
	v_mfma_f32_32x32x16_bf16 v[16:31], v[216:219], v[132:135], v[16:31]
	ds_read_b128 v[204:207], v248 offset:8192
	ds_read_b128 v[216:219], v249 offset:8192
	v_exp_f32_e32 v174, v174
	v_exp_f32_e32 v175, v175
	v_exp_f32_e32 v176, v176
	s_waitcnt lgkmcnt(4)
	v_mfma_f32_32x32x16_bf16 v[96:111], v[220:223], v[156:159], v[96:111]
	v_exp_f32_e32 v177, v177
	v_exp_f32_e32 v178, v178
	v_exp_f32_e64 v179, v179
	v_mfma_f32_32x32x16_bf16 v[96:111], v[224:227], v[160:163], v[96:111]
	ds_read_b128 v[220:223], v248 offset:12288
	ds_read_b128 v[224:227], v249 offset:12288
	v_exp_f32_e32 v180, v180
	v_exp_f32_e32 v181, v181
	v_exp_f32_e32 v182, v182
	s_waitcnt lgkmcnt(4)
	v_mfma_f32_32x32x16_bf16 v[64:79], v[188:191], v[156:159], v[64:79]
	v_exp_f32_e32 v183, v183
	v_exp_f32_e32 v184, v184
	v_exp_f32_e64 v185, v185
	v_mfma_f32_32x32x16_bf16 v[64:79], v[200:203], v[160:163], v[64:79]
	v_xad_u32 v248, v198, 64, s60
	v_xor_b32_e32 v249, 0x60, v198
	v_add_u32_e32 v249, s60, v249
	ds_read_b128 v[188:191], v248
	ds_read_b128 v[200:203], v249
	v_exp_f32_e32 v186, v186
	v_exp_f32_e32 v187, v187
	v_add_f32_e32 v192, v172, v173
	v_add_f32_e32 v193, v174, v175
	v_add_f32_e64 v192, v192, v176
	s_waitcnt lgkmcnt(4)
	v_mfma_f32_32x32x16_bf16 v[32:47], v[204:207], v[156:159], v[32:47]
	v_add_f32_e32 v193, v193, v177
	v_add_f32_e32 v192, v192, v178
	v_add_f32_e32 v193, v193, v179
	v_add_f32_e32 v192, v192, v180
	v_add_f32_e32 v193, v193, v181
	v_add_f32_e32 v192, v192, v182
	v_add_f32_e64 v193, v193, v183
	v_mfma_f32_32x32x16_bf16 v[32:47], v[216:219], v[160:163], v[32:47]
	ds_read_b128 v[204:207], v248 offset:4096
	ds_read_b128 v[216:219], v249 offset:4096
	v_add_f32_e32 v192, v192, v184
	v_add_f32_e32 v193, v193, v185
	v_add_f32_e32 v192, v192, v186
	v_add_f32_e32 v193, v193, v187
	v_add_f32_e32 v192, v192, v193
	v_add_f32_e64 v150, v150, v192
	v_cvt_pk_bf16_f32 v172, v172, v173
	s_waitcnt lgkmcnt(4)
	v_mfma_f32_32x32x16_bf16 v[0:15], v[220:223], v[156:159], v[0:15]
	v_cvt_pk_bf16_f32 v173, v174, v175
	v_cvt_pk_bf16_f32 v174, v176, v177
	v_cvt_pk_bf16_f32 v175, v178, v179
	v_cvt_pk_bf16_f32 v176, v180, v181
	v_cvt_pk_bf16_f32 v177, v182, v183
	v_cvt_pk_bf16_f32 v178, v184, v185
	v_cvt_pk_bf16_f32 v179, v186, v187
	v_mfma_f32_32x32x16_bf16 v[0:15], v[224:227], v[160:163], v[0:15]
	ds_read_b128 v[220:223], v248 offset:8192
	ds_read_b128 v[224:227], v249 offset:8192
	v_exp_f32_e32 v228, v228
	v_exp_f32_e32 v229, v229
	v_exp_f32_e32 v230, v230
	s_waitcnt lgkmcnt(4)
	v_mfma_f32_32x32x16_bf16 v[112:127], v[188:191], v[172:175], v[112:127]
	v_exp_f32_e32 v231, v231
	v_exp_f32_e32 v232, v232
	v_exp_f32_e64 v233, v233
	v_mfma_f32_32x32x16_bf16 v[112:127], v[200:203], v[176:179], v[112:127]
	ds_read_b128 v[188:191], v248 offset:12288
	ds_read_b128 v[200:203], v249 offset:12288
	v_exp_f32_e32 v234, v234
	v_exp_f32_e32 v235, v235
	v_exp_f32_e32 v236, v236
	s_waitcnt lgkmcnt(4)
	v_mfma_f32_32x32x16_bf16 v[80:95], v[204:207], v[172:175], v[80:95]
	v_exp_f32_e32 v237, v237
	v_exp_f32_e32 v238, v238
	v_exp_f32_e64 v239, v239
	v_mfma_f32_32x32x16_bf16 v[80:95], v[216:219], v[176:179], v[80:95]
	ds_read_b128 v[204:207], v248
	ds_read_b128 v[216:219], v249
	v_exp_f32_e32 v240, v240
	v_exp_f32_e32 v241, v241
	v_exp_f32_e32 v242, v242
	s_waitcnt lgkmcnt(4)
	v_mfma_f32_32x32x16_bf16 v[48:63], v[220:223], v[172:175], v[48:63]
	v_exp_f32_e32 v243, v243
	v_add_f32_e32 v192, v228, v229
	v_add_f32_e32 v193, v230, v231
	v_add_f32_e32 v192, v192, v232
	v_add_f32_e32 v193, v193, v233
	v_add_f32_e32 v192, v192, v234
	v_mfma_f32_32x32x16_bf16 v[48:63], v[224:227], v[176:179], v[48:63]
	ds_read_b128 v[220:223], v248 offset:4096
	ds_read_b128 v[224:227], v249 offset:4096
	v_add_f32_e32 v193, v193, v235
	v_add_f32_e32 v192, v192, v236
	v_add_f32_e32 v193, v193, v237
	v_add_f32_e32 v192, v192, v238
	v_add_f32_e32 v193, v193, v239
	v_add_f32_e32 v192, v192, v240
	v_add_f32_e32 v193, v193, v241
	s_waitcnt lgkmcnt(4)
	v_mfma_f32_32x32x16_bf16 v[16:31], v[188:191], v[172:175], v[16:31]
	v_add_f32_e32 v192, v192, v242
	v_add_f32_e32 v193, v193, v243
	v_add_f32_e32 v192, v192, v193
	v_add_f32_e32 v151, v151, v192
	v_cvt_pk_bf16_f32 v228, v228, v229
	v_cvt_pk_bf16_f32 v229, v230, v231
	v_cvt_pk_bf16_f32 v230, v232, v233
	v_mfma_f32_32x32x16_bf16 v[16:31], v[200:203], v[176:179], v[16:31]
	ds_read_b128 v[188:191], v248 offset:8192
	ds_read_b128 v[200:203], v249 offset:8192
	v_cvt_pk_bf16_f32 v231, v234, v235
	v_cvt_pk_bf16_f32 v232, v236, v237
	v_cvt_pk_bf16_f32 v233, v238, v239
	v_cvt_pk_bf16_f32 v234, v240, v241
	v_cvt_pk_bf16_f32 v235, v242, v243
	s_waitcnt lgkmcnt(4)
	v_mfma_f32_32x32x16_bf16 v[96:111], v[204:207], v[228:231], v[96:111]
	v_mfma_f32_32x32x16_bf16 v[96:111], v[216:219], v[232:235], v[96:111]
	ds_read_b128 v[204:207], v248 offset:12288
	ds_read_b128 v[216:219], v249 offset:12288
	s_waitcnt lgkmcnt(4)
	v_mfma_f32_32x32x16_bf16 v[64:79], v[220:223], v[228:231], v[64:79]
	v_mfma_f32_32x32x16_bf16 v[64:79], v[224:227], v[232:235], v[64:79]
	s_waitcnt lgkmcnt(2)
	v_mfma_f32_32x32x16_bf16 v[32:47], v[188:191], v[228:231], v[32:47]
	v_mfma_f32_32x32x16_bf16 v[32:47], v[200:203], v[232:235], v[32:47]
	s_waitcnt lgkmcnt(0)
	v_mfma_f32_32x32x16_bf16 v[0:15], v[204:207], v[228:231], v[0:15]
	v_mfma_f32_32x32x16_bf16 v[0:15], v[216:219], v[232:235], v[0:15]
	s_mov_b64 s[92:93], -1
	s_and_b64 vcc, exec, s[86:87]
	s_cbranch_vccnz .LBB0_38
